# v23 + nt on the P7 x1 stores (re-read only two phases later; keeps h2 cache-resident for P9)
# baseline (speedup 1.0000x reference)
;     __device__ __forceinline__ void operator()(f32x4 (&acc)[2][2][4][2], const Unit& u, int wr, int wc, int fr, int fq) const {
;     ...
;         for (int bj = 0; bj < 2; ++bj) {
;             const int col = col0 + bj * HALF;
;             const f32x4 g0 = *(const f32x4*)(gate + (size_t)b * ADAW + col), g1 = *(const f32x4*)(gate + (size_t)b * ADAW + col + 4);
; #pragma unroll
;             for (int ai = 0; ai < 2; ++ai)
; #pragma unroll
;                 for (int m = 0; m < 4; ++m) {
;                     const size_t off = (size_t)(row0 + ai * HALF + m * 16) * D + col;
;                     const f32x4 x0 = *(const f32x4*)(base + off) + g0 * acc[ai][bj][m][0], x1 = *(const f32x4*)(base + off + 4) + g1 * acc[ai][bj][m][1];
;                     *(f32x4*)(out + off) = x0; *(f32x4*)(out + off + 4) = x1;
;                     acc[ai][bj][m][0] = x0; acc[ai][bj][m][1] = x1;
.LBB0_740:
	s_ashr_i32 s2, s20, 31
	s_lshr_b32 s2, s2, 28
	s_add_i32 s2, s20, s2
	v_lshl_add_u32 v204, s20, 8, v212
	s_ashr_i32 s3, s2, 4
	v_lshl_add_u32 v202, s0, 8, v214
	s_mul_hi_i32 s2, s3, 0x6000
	s_mulk_i32 s3, 0x6000
	v_ashrrev_i32_e32 v205, 31, v204
	s_add_u32 s22, s54, s3
	v_ashrrev_i32_e32 v203, 31, v202
	v_lshlrev_b64 v[128:129], 10, v[204:205]
	s_addc_u32 s23, s55, s2
	v_lshl_add_u64 v[128:129], v[128:129], 0, v[202:203]
	v_readlane_b32 s72, v242, 18
	v_lshl_add_u64 v[144:145], v[202:203], 2, s[22:23]
	v_lshlrev_b64 v[132:133], 2, v[128:129]
	v_readlane_b32 s73, v242, 19
	global_load_dwordx4 v[136:139], v[144:145], off
	v_or_b32_e32 v198, 16, v204
	v_lshl_add_u64 v[176:177], s[72:73], 0, v[132:133]
	global_load_dwordx4 v[128:131], v[176:177], off nt
	global_load_dwordx4 v[146:149], v[176:177], off offset:16 nt
	global_load_dwordx4 v[140:143], v[144:145], off offset:16
	v_ashrrev_i32_e32 v199, 31, v198
	v_lshlrev_b64 v[134:135], 10, v[198:199]
	v_lshl_add_u64 v[134:135], v[134:135], 0, v[202:203]
	v_lshl_add_u64 v[180:181], s[26:27], 0, v[132:133]
	v_lshlrev_b64 v[150:151], 2, v[134:135]
	v_lshl_add_u64 v[178:179], s[72:73], 0, v[150:151]
	v_or_b32_e32 v194, 32, v204
	v_ashrrev_i32_e32 v195, 31, v194
	v_lshl_add_u64 v[184:185], s[26:27], 0, v[150:151]
	v_or_b32_e32 v190, 48, v204
	v_ashrrev_i32_e32 v191, 31, v190
	v_add_u32_e32 v186, 0x80, v204
	v_ashrrev_i32_e32 v187, 31, v186
	v_add_u32_e32 v174, 0x90, v204
	v_ashrrev_i32_e32 v175, 31, v174
	v_add_u32_e32 v172, 0xa0, v204
	v_ashrrev_i32_e32 v173, 31, v172
	v_add_u32_e32 v170, 0xb0, v204
	v_ashrrev_i32_e32 v171, 31, v170
	s_lshl_b32 s22, s0, 2
	s_ashr_i32 s23, s22, 31
	v_readlane_b32 s74, v242, 20
	v_readlane_b32 s75, v242, 21
	v_readlane_b32 s76, v242, 22
	v_readlane_b32 s77, v242, 23
	v_readlane_b32 s78, v242, 24
	v_readlane_b32 s79, v242, 25
	v_readlane_b32 s80, v242, 26
	v_readlane_b32 s81, v242, 27
	v_readlane_b32 s82, v242, 28
	v_readlane_b32 s83, v242, 29
	v_readlane_b32 s84, v242, 30
	v_readlane_b32 s85, v242, 31
	v_readlane_b32 s86, v242, 32
	v_readlane_b32 s87, v242, 33
	s_waitcnt vmcnt(0)
	v_pk_fma_f32 v[134:135], v[126:127], v[138:139], v[130:131]
	v_pk_fma_f32 v[132:133], v[124:125], v[136:137], v[128:129]
	v_pk_fma_f32 v[130:131], v[122:123], v[142:143], v[148:149]
	v_pk_fma_f32 v[128:129], v[120:121], v[140:141], v[146:147]
	global_store_dwordx4 v[180:181], v[132:135], off nt
	global_store_dwordx4 v[180:181], v[128:131], off offset:16 nt
	global_load_dwordx4 v[120:123], v[178:179], off nt
	global_load_dwordx4 v[124:127], v[178:179], off offset:16 nt
	v_lshlrev_b64 v[146:147], 10, v[194:195]
	v_lshl_add_u64 v[146:147], v[146:147], 0, v[202:203]
	v_lshlrev_b64 v[146:147], 2, v[146:147]
	v_lshl_add_u64 v[182:183], s[72:73], 0, v[146:147]
	v_lshlrev_b64 v[148:149], 10, v[190:191]
	v_lshl_add_u64 v[148:149], v[148:149], 0, v[202:203]
	v_lshlrev_b64 v[148:149], 2, v[148:149]
	v_lshl_add_u64 v[192:193], s[26:27], 0, v[146:147]
	v_lshl_add_u64 v[188:189], s[72:73], 0, v[148:149]
	v_lshlrev_b64 v[146:147], 10, v[186:187]
	v_lshl_add_u64 v[146:147], v[146:147], 0, v[202:203]
	v_lshlrev_b64 v[146:147], 2, v[146:147]
	v_lshl_add_u64 v[206:207], s[26:27], 0, v[148:149]
	v_lshl_add_u64 v[196:197], s[72:73], 0, v[146:147]
	v_lshlrev_b64 v[148:149], 10, v[174:175]
	v_lshl_add_u64 v[148:149], v[148:149], 0, v[202:203]
	v_lshlrev_b64 v[148:149], 2, v[148:149]
	v_lshl_add_u64 v[210:211], s[26:27], 0, v[146:147]
	v_lshl_add_u64 v[208:209], s[72:73], 0, v[148:149]
	v_lshlrev_b64 v[146:147], 10, v[172:173]
	v_lshl_add_u64 v[146:147], v[146:147], 0, v[202:203]
	v_lshlrev_b64 v[146:147], 2, v[146:147]
	v_lshl_add_u64 v[220:221], s[26:27], 0, v[148:149]
	v_lshl_add_u64 v[222:223], s[72:73], 0, v[146:147]
	v_lshlrev_b64 v[148:149], 10, v[170:171]
	v_lshl_add_u64 v[148:149], v[148:149], 0, v[202:203]
	v_lshlrev_b64 v[148:149], 2, v[148:149]
	v_lshl_add_u64 v[224:225], s[26:27], 0, v[146:147]
	v_lshl_add_u64 v[226:227], s[72:73], 0, v[148:149]
	v_lshl_add_u64 v[200:201], s[26:27], 0, v[148:149]
	s_waitcnt vmcnt(1)
	v_pk_fma_f32 v[118:119], v[118:119], v[138:139], v[122:123]
	v_pk_fma_f32 v[116:117], v[116:117], v[136:137], v[120:121]
	s_waitcnt vmcnt(0)
	v_pk_fma_f32 v[114:115], v[114:115], v[142:143], v[126:127]
	v_pk_fma_f32 v[112:113], v[112:113], v[140:141], v[124:125]
	global_store_dwordx4 v[184:185], v[116:119], off nt
	global_store_dwordx4 v[184:185], v[112:115], off offset:16 nt
	global_load_dwordx4 v[120:123], v[182:183], off nt
	global_load_dwordx4 v[124:127], v[182:183], off offset:16 nt
	s_waitcnt vmcnt(1)
	v_pk_fma_f32 v[102:103], v[102:103], v[138:139], v[122:123]
	v_pk_fma_f32 v[100:101], v[100:101], v[136:137], v[120:121]
	s_waitcnt vmcnt(0)
	v_pk_fma_f32 v[98:99], v[98:99], v[142:143], v[126:127]
	v_pk_fma_f32 v[96:97], v[96:97], v[140:141], v[124:125]
	global_store_dwordx4 v[192:193], v[100:103], off nt
	global_store_dwordx4 v[192:193], v[96:99], off offset:16 nt
	global_load_dwordx4 v[120:123], v[188:189], off nt
	global_load_dwordx4 v[124:127], v[188:189], off offset:16 nt
	s_waitcnt vmcnt(1)
	v_pk_fma_f32 v[86:87], v[86:87], v[138:139], v[122:123]
	v_pk_fma_f32 v[84:85], v[84:85], v[136:137], v[120:121]
	s_waitcnt vmcnt(0)
	v_pk_fma_f32 v[82:83], v[82:83], v[142:143], v[126:127]
	v_pk_fma_f32 v[80:81], v[80:81], v[140:141], v[124:125]
	global_store_dwordx4 v[206:207], v[84:87], off nt
	global_store_dwordx4 v[206:207], v[80:83], off offset:16 nt
	global_load_dwordx4 v[120:123], v[196:197], off nt
	global_load_dwordx4 v[124:127], v[196:197], off offset:16 nt
	s_waitcnt vmcnt(1)
	v_pk_fma_f32 v[70:71], v[70:71], v[138:139], v[122:123]
	v_pk_fma_f32 v[68:69], v[68:69], v[136:137], v[120:121]
	s_waitcnt vmcnt(0)
;     __device__ __forceinline__ void operator()(f32x4 (&acc)[2][2][4][2], const Unit& u, int wr, int wc, int fr, int fq) const {
;     ...
;             const f32x4 g0 = *(const f32x4*)(gate + (size_t)b * ADAW + col), g1 = *(const f32x4*)(gate + (size_t)b * ADAW + col + 4);
; #pragma unroll
;             for (int ai = 0; ai < 2; ++ai)
; #pragma unroll
;                 for (int m = 0; m < 4; ++m) {
;                     const size_t off = (size_t)(row0 + ai * HALF + m * 16) * D + col;
;                     const f32x4 x0 = *(const f32x4*)(base + off) + g0 * acc[ai][bj][m][0], x1 = *(const f32x4*)(base + off + 4) + g1 * acc[ai][bj][m][1];
;                     *(f32x4*)(out + off) = x0; *(f32x4*)(out + off + 4) = x1;
;                     acc[ai][bj][m][0] = x0; acc[ai][bj][m][1] = x1;
;                 }
;         }
; #pragma unroll
;         for (int ai = 0; ai < 2; ++ai)
; #pragma unroll
;             for (int m = 0; m < 4; ++m) {
;                 float s = 0.f;
; #pragma unroll
;                 for (int bj = 0; bj < 2; ++bj)
; #pragma unroll
;                     for (int n = 0; n < 2; ++n) { const f32x4 v = acc[ai][bj][m][n]; s += (v[0] * v[0] + v[1] * v[1]) + (v[2] * v[2] + v[3] * v[3]); }
;                 s = rows4_sum(s);
	v_pk_fma_f32 v[66:67], v[66:67], v[142:143], v[126:127]
	v_pk_fma_f32 v[64:65], v[64:65], v[140:141], v[124:125]
	global_store_dwordx4 v[210:211], v[68:71], off nt
	global_store_dwordx4 v[210:211], v[64:67], off offset:16 nt
	global_load_dwordx4 v[120:123], v[208:209], off nt
	global_load_dwordx4 v[124:127], v[208:209], off offset:16 nt
	s_waitcnt vmcnt(1)
	v_pk_fma_f32 v[38:39], v[38:39], v[138:139], v[122:123]
	v_pk_fma_f32 v[36:37], v[36:37], v[136:137], v[120:121]
	s_waitcnt vmcnt(0)
	v_pk_fma_f32 v[34:35], v[34:35], v[142:143], v[126:127]
	v_pk_fma_f32 v[32:33], v[32:33], v[140:141], v[124:125]
	global_store_dwordx4 v[220:221], v[36:39], off nt
	global_store_dwordx4 v[220:221], v[32:35], off offset:16 nt
	global_load_dwordx4 v[120:123], v[222:223], off nt
	global_load_dwordx4 v[124:127], v[222:223], off offset:16 nt
	s_waitcnt vmcnt(1)
	v_pk_fma_f32 v[22:23], v[22:23], v[138:139], v[122:123]
	v_pk_fma_f32 v[20:21], v[20:21], v[136:137], v[120:121]
	s_waitcnt vmcnt(0)
	v_pk_fma_f32 v[18:19], v[18:19], v[142:143], v[126:127]
	v_pk_fma_f32 v[16:17], v[16:17], v[140:141], v[124:125]
	global_store_dwordx4 v[224:225], v[20:23], off nt
	global_store_dwordx4 v[224:225], v[16:19], off offset:16 nt
	global_load_dwordx4 v[120:123], v[226:227], off nt
	global_load_dwordx4 v[124:127], v[226:227], off offset:16 nt
	s_waitcnt vmcnt(1)
	v_pk_fma_f32 v[6:7], v[6:7], v[138:139], v[122:123]
	v_pk_fma_f32 v[4:5], v[4:5], v[136:137], v[120:121]
	s_waitcnt vmcnt(0)
	v_pk_fma_f32 v[2:3], v[2:3], v[142:143], v[126:127]
	v_pk_fma_f32 v[0:1], v[0:1], v[140:141], v[124:125]
	global_store_dwordx4 v[200:201], v[4:7], off nt
	global_store_dwordx4 v[200:201], v[0:3], off offset:16 nt
	global_load_dwordx4 v[120:123], v[176:177], off offset:512 nt
	global_load_dwordx4 v[148:151], v[144:145], off offset:512
	s_nop 0
	global_load_dwordx4 v[144:147], v[144:145], off offset:528
	s_nop 0
	global_load_dwordx4 v[124:127], v[176:177], off offset:528 nt
	s_waitcnt vmcnt(2)
	v_pk_fma_f32 v[138:139], v[110:111], v[150:151], v[122:123]
	v_pk_fma_f32 v[136:137], v[108:109], v[148:149], v[120:121]
	s_waitcnt vmcnt(0)
	v_pk_fma_f32 v[142:143], v[106:107], v[146:147], v[126:127]
	v_pk_fma_f32 v[140:141], v[104:105], v[144:145], v[124:125]
	global_store_dwordx4 v[180:181], v[136:139], off offset:512 nt
	global_store_dwordx4 v[180:181], v[140:143], off offset:528 nt
	global_load_dwordx4 v[104:107], v[178:179], off offset:512 nt
	global_load_dwordx4 v[108:111], v[178:179], off offset:528 nt
	s_waitcnt vmcnt(1)
	v_pk_fma_f32 v[122:123], v[94:95], v[150:151], v[106:107]
	v_pk_fma_f32 v[120:121], v[92:93], v[148:149], v[104:105]
	s_waitcnt vmcnt(0)
	v_pk_fma_f32 v[126:127], v[90:91], v[146:147], v[110:111]
	v_pk_fma_f32 v[124:125], v[88:89], v[144:145], v[108:109]
	global_store_dwordx4 v[184:185], v[120:123], off offset:512 nt
	global_store_dwordx4 v[184:185], v[124:127], off offset:528 nt
	global_load_dwordx4 v[88:91], v[182:183], off offset:512 nt
	global_load_dwordx4 v[92:95], v[182:183], off offset:528 nt
	s_waitcnt vmcnt(1)
	v_pk_fma_f32 v[106:107], v[78:79], v[150:151], v[90:91]
	v_pk_fma_f32 v[104:105], v[76:77], v[148:149], v[88:89]
	s_waitcnt vmcnt(0)
	v_pk_fma_f32 v[110:111], v[74:75], v[146:147], v[94:95]
	v_pk_fma_f32 v[108:109], v[72:73], v[144:145], v[92:93]
	global_store_dwordx4 v[192:193], v[104:107], off offset:512 nt
	global_store_dwordx4 v[192:193], v[108:111], off offset:528 nt
	global_load_dwordx4 v[72:75], v[188:189], off offset:512 nt
	global_load_dwordx4 v[76:79], v[188:189], off offset:528 nt
	s_waitcnt vmcnt(1)
	v_pk_fma_f32 v[90:91], v[62:63], v[150:151], v[74:75]
	v_pk_fma_f32 v[88:89], v[60:61], v[148:149], v[72:73]
	s_waitcnt vmcnt(0)
	v_pk_fma_f32 v[94:95], v[58:59], v[146:147], v[78:79]
	v_pk_fma_f32 v[92:93], v[56:57], v[144:145], v[76:77]
	global_store_dwordx4 v[206:207], v[88:91], off offset:512 nt
	global_store_dwordx4 v[206:207], v[92:95], off offset:528 nt
	global_load_dwordx4 v[56:59], v[196:197], off offset:512 nt
	global_load_dwordx4 v[60:63], v[196:197], off offset:528 nt
	s_waitcnt vmcnt(1)
	v_pk_fma_f32 v[74:75], v[54:55], v[150:151], v[58:59]
	v_pk_fma_f32 v[72:73], v[52:53], v[148:149], v[56:57]
	s_waitcnt vmcnt(0)
	v_pk_fma_f32 v[78:79], v[50:51], v[146:147], v[62:63]
	v_pk_fma_f32 v[76:77], v[48:49], v[144:145], v[60:61]
	global_store_dwordx4 v[210:211], v[72:75], off offset:512 nt
	global_store_dwordx4 v[210:211], v[76:79], off offset:528 nt
	global_load_dwordx4 v[48:51], v[208:209], off offset:512 nt
	global_load_dwordx4 v[52:55], v[208:209], off offset:528 nt
	v_mul_f32_e32 v60, v143, v143
	v_fmac_f32_e32 v60, v142, v142
	v_lshlrev_b64 v[210:211], 6, v[204:205]
	s_waitcnt vmcnt(1)
	v_pk_fma_f32 v[50:51], v[46:47], v[150:151], v[50:51]
	v_pk_fma_f32 v[48:49], v[44:45], v[148:149], v[48:49]
	s_waitcnt vmcnt(0)
	v_pk_fma_f32 v[54:55], v[42:43], v[146:147], v[54:55]
	v_pk_fma_f32 v[52:53], v[40:41], v[144:145], v[52:53]
	global_store_dwordx4 v[220:221], v[48:51], off offset:512 nt
	global_store_dwordx4 v[220:221], v[52:55], off offset:528 nt
	global_load_dwordx4 v[40:43], v[222:223], off offset:512 nt
	global_load_dwordx4 v[44:47], v[222:223], off offset:528 nt
	s_waitcnt vmcnt(1)
	v_pk_fma_f32 v[26:27], v[26:27], v[150:151], v[42:43]
	v_pk_fma_f32 v[24:25], v[24:25], v[148:149], v[40:41]
	s_waitcnt vmcnt(0)
	v_pk_fma_f32 v[30:31], v[30:31], v[146:147], v[46:47]
	v_pk_fma_f32 v[28:29], v[28:29], v[144:145], v[44:45]
	global_store_dwordx4 v[224:225], v[24:27], off offset:512 nt
	global_store_dwordx4 v[224:225], v[28:31], off offset:528 nt
	global_load_dwordx4 v[42:45], v[226:227], off offset:512 nt
	global_load_dwordx4 v[56:59], v[226:227], off offset:528 nt
	v_mul_f32_e32 v40, v133, v133
	v_mul_f32_e32 v41, v135, v135
	v_mul_f32_e32 v46, v129, v129
	v_mul_f32_e32 v47, v131, v131
	v_fmac_f32_e32 v40, v132, v132
	v_fmac_f32_e32 v41, v134, v134
	v_fmac_f32_e32 v46, v128, v128
	v_fmac_f32_e32 v47, v130, v130
	v_add_f32_e32 v40, v40, v41
	v_add_f32_e32 v41, v46, v47
	v_add_f32_e32 v40, v40, v41
	v_mul_f32_e32 v41, v137, v137
	v_mul_f32_e32 v46, v139, v139
	v_mul_f32_e32 v47, v141, v141
	v_fmac_f32_e32 v41, v136, v136
	v_fmac_f32_e32 v46, v138, v138
	v_fmac_f32_e32 v47, v140, v140
	v_add_f32_e32 v41, v41, v46
	v_add_f32_e32 v46, v47, v60
	v_add_f32_e32 v40, v40, v41
	v_add_f32_e32 v40, v40, v46
	v_mov_b32_e32 v41, v40
	s_nop 1
	v_permlane32_swap_b32_e32 v40, v41
	v_add_f32_e32 v40, v40, v41
	v_mov_b32_e32 v41, v40
	s_nop 1
	v_permlane16_swap_b32_e32 v40, v41
	s_waitcnt vmcnt(1)
	v_pk_fma_f32 v[14:15], v[14:15], v[150:151], v[44:45]
	v_pk_fma_f32 v[12:13], v[12:13], v[148:149], v[42:43]
	s_waitcnt vmcnt(0)
	v_pk_fma_f32 v[10:11], v[10:11], v[146:147], v[58:59]
	v_pk_fma_f32 v[8:9], v[8:9], v[144:145], v[56:57]
	global_store_dwordx4 v[200:201], v[12:15], off offset:512 nt
	global_store_dwordx4 v[200:201], v[8:11], off offset:528 nt
	s_and_saveexec_b64 s[24:25], s[40:41]
	s_cbranch_execz .LBB0_742
; __device__ __forceinline__ float rows4_sum(float v) {
;     ...
;     { auto r = __builtin_amdgcn_permlane16_swap(__float_as_uint(v), __float_as_uint(v), false, false); v = __uint_as_float(r[0]) + __uint_as_float(r[1]); }
;     return v;
;     __device__ __forceinline__ void operator()(f32x4 (&acc)[2][2][4][2], const Unit& u, int wr, int wc, int fr, int fq) const {
;     ...
;                 s = rows4_sum(s);
;                 if (fq == 0) __hip_atomic_store(slots + (size_t)(row0 + ai * HALF + m * 16) * 16 + u.pn * 4 + wc, s, __ATOMIC_RELAXED, __HIP_MEMORY_SCOPE_AGENT);
	v_add_f32_e32 v42, v40, v41
	v_lshl_add_u64 v[40:41], s[8:9], 0, v[210:211]
	v_lshl_add_u64 v[40:41], s[22:23], 2, v[40:41]
	s_lshl_b32 s0, s58, 2
	v_lshl_add_u64 v[40:41], v[40:41], 0, s[0:1]
	global_store_dword v[40:41], v42, off sc1
